# LRU pass<false>: prefetch-draining vmcnt(0) waits relaxed to vmcnt(5); on top of v14 (epilogue rs-load hoists, attention softmax/tr-read/ds_write re-placement)
# baseline (speedup 1.0000x reference)
; template <bool FINAL> ...
;     ...
;         LDS_BAR();
;         u32x4 yv0 = (u32x4){0u, 0u, 0u, 0u}, yv1 = yv0;
;         if (FINAL) { if (pr < 24) { yv0 = *(const u32x4*)(Y + (row0 + 2 * pr) * DM + n * 128 + cgp * 8); yv1 = *(const u32x4*)(Y + (row0 + 2 * pr + 1) * DM + n * 128 + cgp * 8); } }
;         f32x4 acc[3][2][2];
; #pragma unroll
;         for (int mt = 0; mt < 3; ++mt)
; #pragma unroll
;             for (int g = 0; g < 2; ++g)
; #pragma unroll
;                 for (int nt = 0; nt < 2; ++nt) acc[mt][g][nt] = (f32x4){0.f, 0.f, 0.f, 0.f};
; #pragma unroll
;         for (int ks = 0; ks < 4; ++ks) {
; #pragma unroll
;             for (int mt = 0; mt < 3; ++mt) { const bf16x8 af = *(const LAS bf16x8*)(XCB + (mt * 16 + fr) * 272 + (ks * 32 + fq * 8) * 2);
; #pragma unroll
;                 for (int g = 0; g < 2; ++g)
; #pragma unroll
;                     for (int nt = 0; nt < 2; ++nt) acc[mt][g][nt] = __builtin_amdgcn_mfma_f32_16x16x32_bf16(af, w.f[g][nt][ks], acc[mt][g][nt], 0, 0, 0); } }
; #pragma unroll
;         for (int nt = 0; nt < 2; ++nt) { const int ch = cq * 32 + nt * 16 + fr;
;             const float nbr = -1.4426950408889634f * cc.br[nt], nbi = -1.4426950408889634f * cc.bi[nt], k8 = cc.k8[nt];
; #pragma unroll
;             for (int mt = 0; mt < 3; ++mt)
; #pragma unroll
;                 for (int ip = 0; ip < 4; ip += 2) { const int tk = mt * 16 + fq * 4 + ip;
;                     const f32x2 xr2 = (f32x2){acc[mt][0][nt][ip], acc[mt][0][nt][ip + 1]}, xi2 = (f32x2){acc[mt][1][nt][ip], acc[mt][1][nt][ip + 1]};
;                     const f32x2 tr = xr2 * (-1.4426950408889634f) + nbr, ti = xi2 * (-1.4426950408889634f) + nbi;
;                     f32x2 er, ei; er.x = __builtin_amdgcn_exp2f(tr.x); er.y = __builtin_amdgcn_exp2f(tr.y); ei.x = __builtin_amdgcn_exp2f(ti.x); ei.y = __builtin_amdgcn_exp2f(ti.y);
;                     er = er + 1.0f; ei = ei + 1.0f;
;                     f32x2 r, ig; r.x = __builtin_amdgcn_rcpf(er.x); r.y = __builtin_amdgcn_rcpf(er.y); ig.x = __builtin_amdgcn_rcpf(ei.x); ig.y = __builtin_amdgcn_rcpf(ei.y);
;                     const f32x2 la = r * k8;
;                     f32x2 a; a.x = __builtin_amdgcn_exp2f(la.x); a.y = __builtin_amdgcn_exp2f(la.y);
;                     const f32x2 y = 1.0f - a * a;
;                     f32x2 sq; sq.x = __builtin_amdgcn_sqrtf(y.x); sq.y = __builtin_amdgcn_sqrtf(y.y);
.LBB0_641:
	s_or_b64 exec, exec, s[28:29]
	s_mul_i32 s0, s39, 0xfffffaa8
	s_add_i32 s0, s0, s38
	s_ashr_i32 s1, s0, 31
	s_lshl_b64 s[0:1], s[0:1], 11
	s_ashr_i32 s2, s78, 31
	s_add_u32 s3, s74, s78
	s_addc_u32 s2, s75, s2
	v_or_b32_e32 v84, s3, v169
	v_mov_b32_e32 v85, s2
	v_lshl_add_u64 v[130:131], v[84:85], 0, s[0:1]
	v_mul_u32_u24_e32 v84, 0x110, v169
	s_waitcnt lgkmcnt(0)
	s_barrier
	s_waitcnt lgkmcnt(0)
	v_add3_u32 v128, 0, v86, v84
	ds_read_b128 v[84:87], v128 offset:24576
	ds_read_b128 v[142:145], v128 offset:24640
	ds_read_b128 v[100:103], v128 offset:28928
	s_waitcnt lgkmcnt(2)
	v_mfma_f32_16x16x32_bf16 v[88:91], v[84:87], v[32:35], 0
	ds_read_b128 v[116:119], v128 offset:33280
	s_mov_b32 s0, 0x3fb8aa3b
	v_bfe_u32 v125, v124, 4, 2
	v_mfma_f32_16x16x32_bf16 v[92:95], v[84:87], v[40:43], 0
	v_and_b32_e32 v170, 63, v124
	s_andn2_b64 vcc, exec, s[76:77]
	v_cmp_gt_u32_e64 s[36:37], 16, v170
	v_mfma_f32_16x16x32_bf16 v[96:99], v[84:87], v[52:55], 0
	v_mfma_f32_16x16x32_bf16 v[84:87], v[84:87], v[68:71], 0
	s_waitcnt lgkmcnt(2)
	v_mfma_f32_16x16x32_bf16 v[88:91], v[142:145], v[28:31], v[88:91]
	v_mfma_f32_16x16x32_bf16 v[92:95], v[142:145], v[36:39], v[92:95]
	v_mfma_f32_16x16x32_bf16 v[96:99], v[142:145], v[56:59], v[96:99]
	v_mfma_f32_16x16x32_bf16 v[84:87], v[142:145], v[72:75], v[84:87]
	ds_read_b128 v[142:145], v128 offset:28992
	s_waitcnt lgkmcnt(2)
	v_mfma_f32_16x16x32_bf16 v[104:107], v[100:103], v[32:35], 0
	v_mfma_f32_16x16x32_bf16 v[108:111], v[100:103], v[40:43], 0
	v_mfma_f32_16x16x32_bf16 v[112:115], v[100:103], v[52:55], 0
	v_mfma_f32_16x16x32_bf16 v[100:103], v[100:103], v[68:71], 0
	s_waitcnt lgkmcnt(0)
	v_mfma_f32_16x16x32_bf16 v[104:107], v[142:145], v[28:31], v[104:107]
	v_mfma_f32_16x16x32_bf16 v[108:111], v[142:145], v[36:39], v[108:111]
	v_mfma_f32_16x16x32_bf16 v[112:115], v[142:145], v[56:59], v[112:115]
	v_mfma_f32_16x16x32_bf16 v[100:103], v[142:145], v[72:75], v[100:103]
	ds_read_b128 v[142:145], v128 offset:33344
	v_mfma_f32_16x16x32_bf16 v[120:123], v[116:119], v[32:35], 0
	v_mfma_f32_16x16x32_bf16 v[134:137], v[116:119], v[40:43], 0
	v_mfma_f32_16x16x32_bf16 v[138:141], v[116:119], v[52:55], 0
	v_mfma_f32_16x16x32_bf16 v[116:119], v[116:119], v[68:71], 0
	s_waitcnt lgkmcnt(0)
	v_mfma_f32_16x16x32_bf16 v[120:123], v[142:145], v[28:31], v[120:123]
	v_mfma_f32_16x16x32_bf16 v[134:137], v[142:145], v[36:39], v[134:137]
	v_mfma_f32_16x16x32_bf16 v[138:141], v[142:145], v[56:59], v[138:141]
	v_mfma_f32_16x16x32_bf16 v[116:119], v[142:145], v[72:75], v[116:119]
	ds_read_b128 v[142:145], v128 offset:24704
	s_waitcnt lgkmcnt(0)
	v_mfma_f32_16x16x32_bf16 v[88:91], v[142:145], v[24:27], v[88:91]
	s_waitcnt vmcnt(5)
	v_mfma_f32_16x16x32_bf16 v[92:95], v[142:145], v[44:47], v[92:95]
	v_mfma_f32_16x16x32_bf16 v[96:99], v[142:145], v[60:63], v[96:99]
	v_mfma_f32_16x16x32_bf16 v[84:87], v[142:145], v[76:79], v[84:87]
	ds_read_b128 v[142:145], v128 offset:29056
	s_waitcnt lgkmcnt(0)
	v_mfma_f32_16x16x32_bf16 v[146:149], v[142:145], v[24:27], v[104:107]
	s_nop 2
	ds_read_b128 v[104:107], v128 offset:24768
	v_mfma_f32_16x16x32_bf16 v[108:111], v[142:145], v[44:47], v[108:111]
	v_mfma_f32_16x16x32_bf16 v[112:115], v[142:145], v[60:63], v[112:115]
	v_mfma_f32_16x16x32_bf16 v[142:145], v[142:145], v[76:79], v[100:103]
	s_nop 2
	ds_read_b128 v[100:103], v128 offset:33408
	s_waitcnt lgkmcnt(1)
	v_mfma_f32_16x16x32_bf16 v[158:161], v[104:107], v[20:23], v[88:91]
	v_mfma_f32_16x16x32_bf16 v[162:165], v[104:107], v[64:67], v[96:99]
	s_nop 1
	ds_read_b128 v[88:91], v128 offset:33472
	s_waitcnt lgkmcnt(1)
	v_mfma_f32_16x16x32_bf16 v[150:153], v[100:103], v[24:27], v[120:123]
	v_mfma_f32_16x16x32_bf16 v[134:137], v[100:103], v[44:47], v[134:137]
	v_mfma_f32_16x16x32_bf16 v[138:141], v[100:103], v[60:63], v[138:141]
	v_mfma_f32_16x16x32_bf16 v[154:157], v[100:103], v[76:79], v[116:119]
	v_mfma_f32_16x16x32_bf16 v[100:103], v[104:107], v[48:51], v[92:95]
	v_mfma_f32_16x16x32_bf16 v[104:107], v[104:107], v[80:83], v[84:87]
	s_nop 2
	ds_read_b128 v[84:87], v128 offset:29120
	v_mul_f32_e32 v128, 0xbfb8aa3b, v166
	s_waitcnt lgkmcnt(0)
	v_mfma_f32_16x16x32_bf16 v[116:119], v[84:87], v[20:23], v[146:149]
	s_nop 7
	v_pk_fma_f32 v[116:117], v[116:117], s[0:1], v[128:129] op_sel_hi:[1,0,0] neg_lo:[1,0,0] neg_hi:[1,0,0]
	v_mfma_f32_16x16x32_bf16 v[92:95], v[84:87], v[48:51], v[108:111]
	v_exp_f32_e32 v116, v116
	v_exp_f32_e32 v117, v117
	v_pk_fma_f32 v[118:119], v[118:119], s[0:1], v[128:129] op_sel_hi:[1,0,0] neg_lo:[1,0,0] neg_hi:[1,0,0]
	v_mfma_f32_16x16x32_bf16 v[120:123], v[84:87], v[64:67], v[112:115]
	v_exp_f32_e32 v118, v118
	v_pk_add_f32 v[116:117], v[116:117], 1.0 op_sel_hi:[1,0]
	v_exp_f32_e32 v119, v119
	v_mfma_f32_16x16x32_bf16 v[96:99], v[84:87], v[80:83], v[142:145]
	v_rcp_f32_e32 v116, v116
	v_rcp_f32_e32 v117, v117
	v_pk_add_f32 v[118:119], v[118:119], 1.0 op_sel_hi:[1,0]
	v_mfma_f32_16x16x32_bf16 v[84:87], v[88:91], v[48:51], v[134:137]
	v_rcp_f32_e32 v118, v118
	v_pk_mul_f32 v[116:117], v[132:133], v[116:117] op_sel_hi:[0,1]
	v_exp_f32_e32 v116, v116
	v_pk_fma_f32 v[134:135], v[158:159], s[0:1], v[128:129] op_sel_hi:[1,0,0] neg_lo:[1,0,0] neg_hi:[1,0,0]
	v_mfma_f32_16x16x32_bf16 v[108:111], v[88:91], v[20:23], v[150:153]
	v_exp_f32_e32 v134, v134
	v_exp_f32_e32 v135, v135
	v_exp_f32_e32 v117, v117
	v_mfma_f32_16x16x32_bf16 v[112:115], v[88:91], v[64:67], v[138:141]
	v_rcp_f32_e32 v119, v119
	v_pk_add_f32 v[134:135], v[134:135], 1.0 op_sel_hi:[1,0]
	s_nop 1
	v_pk_fma_f32 v[108:109], v[108:109], s[0:1], v[128:129] op_sel_hi:[1,0,0] neg_lo:[1,0,0] neg_hi:[1,0,0]
	v_rcp_f32_e32 v134, v134
	v_rcp_f32_e32 v135, v135
	v_mfma_f32_16x16x32_bf16 v[88:91], v[88:91], v[80:83], v[154:157]
	v_lshlrev_b32_e32 v140, 11, v125
	v_lshlrev_b32_e32 v141, 2, v169
	v_pk_mul_f32 v[134:135], v[132:133], v[134:135] op_sel_hi:[0,1]
	v_mul_f32_e32 v154, 0xbfb8aa3b, v133
	v_pk_fma_f32 v[136:137], v[162:163], s[0:1], v[154:155] op_sel_hi:[1,0,0] neg_lo:[1,0,0] neg_hi:[1,0,0]
	v_exp_f32_e32 v134, v134
	v_exp_f32_e32 v136, v136
	v_exp_f32_e32 v137, v137
	v_exp_f32_e32 v135, v135
	v_add3_u32 v155, s70, v141, v140
	ds_read2_b32 v[142:143], v155 offset1:16
	ds_read2_b32 v[144:145], v155 offset0:128 offset1:144
	v_pk_add_f32 v[136:137], v[136:137], 1.0 op_sel_hi:[1,0]
	v_pk_fma_f32 v[138:139], v[134:135], v[134:135], 1.0 op_sel_hi:[1,1,0] neg_lo:[1,0,0] neg_hi:[1,0,0]
	v_rcp_f32_e32 v136, v136
	v_rcp_f32_e32 v137, v137
	v_sqrt_f32_e32 v138, v138
	v_sqrt_f32_e32 v139, v139
	s_waitcnt lgkmcnt(1)
; template <bool FINAL> ...
;     ...
;                 for (int ip = 0; ip < 4; ip += 2) { const int tk = mt * 16 + fq * 4 + ip;
;                     const f32x2 xr2 = (f32x2){acc[mt][0][nt][ip], acc[mt][0][nt][ip + 1]}, xi2 = (f32x2){acc[mt][1][nt][ip], acc[mt][1][nt][ip + 1]};
;                     const f32x2 tr = xr2 * (-1.4426950408889634f) + nbr, ti = xi2 * (-1.4426950408889634f) + nbi;
;                     f32x2 er, ei; er.x = __builtin_amdgcn_exp2f(tr.x); er.y = __builtin_amdgcn_exp2f(tr.y); ei.x = __builtin_amdgcn_exp2f(ti.x); ei.y = __builtin_amdgcn_exp2f(ti.y);
;                     er = er + 1.0f; ei = ei + 1.0f;
;                     f32x2 r, ig; r.x = __builtin_amdgcn_rcpf(er.x); r.y = __builtin_amdgcn_rcpf(er.y); ig.x = __builtin_amdgcn_rcpf(ei.x); ig.y = __builtin_amdgcn_rcpf(ei.y);
;                     const f32x2 la = r * k8;
;                     f32x2 a; a.x = __builtin_amdgcn_exp2f(la.x); a.y = __builtin_amdgcn_exp2f(la.y);
;                     const f32x2 y = 1.0f - a * a;
;                     f32x2 sq; sq.x = __builtin_amdgcn_sqrtf(y.x); sq.y = __builtin_amdgcn_sqrtf(y.y);
;                     const f32x2 xc2 = (f32x2){XCF[tk * 128 + ch], XCF[(tk + 1) * 128 + ch]};
;                     const f32x2 bb = sq * ig * xc2;
;                     acc[mt][0][nt][ip] = a.x; acc[mt][0][nt][ip + 1] = a.y; acc[mt][1][nt][ip] = bb.x; acc[mt][1][nt][ip + 1] = bb.y; } }
	v_mov_b32_e32 v140, v142
	s_waitcnt lgkmcnt(0)
	v_mov_b32_e32 v141, v144
	v_add_u32_e32 v142, 0x400, v155
	v_pk_mul_f32 v[136:137], v[136:137], v[138:139]
	v_pk_fma_f32 v[138:139], v[160:161], s[0:1], v[128:129] op_sel_hi:[1,0,0] neg_lo:[1,0,0] neg_hi:[1,0,0]
	v_pk_mul_f32 v[136:137], v[140:141], v[136:137]
	v_exp_f32_e32 v138, v138
	v_exp_f32_e32 v139, v139
	v_pk_fma_f32 v[140:141], v[164:165], s[0:1], v[154:155] op_sel_hi:[1,0,0] neg_lo:[1,0,0] neg_hi:[1,0,0]
	v_pk_fma_f32 v[120:121], v[120:121], s[0:1], v[154:155] op_sel_hi:[1,0,0] neg_lo:[1,0,0] neg_hi:[1,0,0]
	v_exp_f32_e32 v140, v140
	v_pk_add_f32 v[138:139], v[138:139], 1.0 op_sel_hi:[1,0]
	v_exp_f32_e32 v141, v141
	v_rcp_f32_e32 v138, v138
	v_rcp_f32_e32 v139, v139
	v_exp_f32_e32 v120, v120
	v_pk_add_f32 v[140:141], v[140:141], 1.0 op_sel_hi:[1,0]
	v_exp_f32_e32 v121, v121
	v_pk_mul_f32 v[138:139], v[132:133], v[138:139] op_sel_hi:[0,1]
	v_exp_f32_e32 v138, v138
	v_exp_f32_e32 v139, v139
	v_rcp_f32_e32 v140, v140
	v_rcp_f32_e32 v141, v141
	v_pk_add_f32 v[120:121], v[120:121], 1.0 op_sel_hi:[1,0]
	v_pk_fma_f32 v[146:147], v[138:139], v[138:139], 1.0 op_sel_hi:[1,1,0] neg_lo:[1,0,0] neg_hi:[1,0,0]
	v_rcp_f32_e32 v120, v120
	v_sqrt_f32_e32 v150, v146
	v_sqrt_f32_e32 v151, v147
	ds_read2_b32 v[146:147], v142 offset1:16
	ds_read2_b32 v[148:149], v142 offset0:128 offset1:144
	v_add_u32_e32 v142, 0x2000, v155
	v_rcp_f32_e32 v121, v121
	v_pk_mul_f32 v[140:141], v[140:141], v[150:151]
	s_waitcnt lgkmcnt(1)
	v_mov_b32_e32 v152, v146
	s_waitcnt lgkmcnt(0)
	v_mov_b32_e32 v153, v148
	v_pk_fma_f32 v[150:151], v[116:117], v[116:117], 1.0 op_sel_hi:[1,1,0] neg_lo:[1,0,0] neg_hi:[1,0,0]
	v_pk_mul_f32 v[140:141], v[152:153], v[140:141]
	v_sqrt_f32_e32 v156, v150
	v_sqrt_f32_e32 v157, v151
	ds_read2_b32 v[150:151], v142 offset1:16
	ds_read2_b32 v[152:153], v142 offset0:128 offset1:144
	v_pk_fma_f32 v[122:123], v[122:123], s[0:1], v[154:155] op_sel_hi:[1,0,0] neg_lo:[1,0,0] neg_hi:[1,0,0]
	v_pk_mul_f32 v[118:119], v[132:133], v[118:119] op_sel_hi:[0,1]
	v_exp_f32_e32 v122, v122
	v_exp_f32_e32 v123, v123
	v_exp_f32_e32 v118, v118
	v_exp_f32_e32 v119, v119
	v_exp_f32_e32 v108, v108
	v_exp_f32_e32 v109, v109
	s_waitcnt lgkmcnt(1)
	v_mov_b32_e32 v158, v150
	s_waitcnt lgkmcnt(0)
	v_mov_b32_e32 v159, v152
	v_pk_mul_f32 v[120:121], v[120:121], v[156:157]
	v_add_u32_e32 v142, 0x2400, v155
	v_pk_mul_f32 v[120:121], v[158:159], v[120:121]
	v_pk_add_f32 v[122:123], v[122:123], 1.0 op_sel_hi:[1,0]
	v_pk_fma_f32 v[156:157], v[118:119], v[118:119], 1.0 op_sel_hi:[1,1,0] neg_lo:[1,0,0] neg_hi:[1,0,0]
	ds_read2_b32 v[158:159], v142 offset1:16
	ds_read2_b32 v[160:161], v142 offset0:128 offset1:144
	v_pk_add_f32 v[108:109], v[108:109], 1.0 op_sel_hi:[1,0]
	v_pk_fma_f32 v[110:111], v[110:111], s[0:1], v[128:129] op_sel_hi:[1,0,0] neg_lo:[1,0,0] neg_hi:[1,0,0]
	v_rcp_f32_e32 v122, v122
	v_rcp_f32_e32 v123, v123
	v_sqrt_f32_e32 v156, v156
	v_sqrt_f32_e32 v157, v157
	v_rcp_f32_e32 v108, v108
	v_rcp_f32_e32 v109, v109
	v_exp_f32_e32 v110, v110
	v_exp_f32_e32 v111, v111
	s_waitcnt lgkmcnt(1)
	v_mov_b32_e32 v162, v158
	s_waitcnt lgkmcnt(0)
	v_mov_b32_e32 v163, v160
	v_pk_mul_f32 v[122:123], v[122:123], v[156:157]
	v_pk_fma_f32 v[112:113], v[112:113], s[0:1], v[154:155] op_sel_hi:[1,0,0] neg_lo:[1,0,0] neg_hi:[1,0,0]
	v_pk_mul_f32 v[108:109], v[132:133], v[108:109] op_sel_hi:[0,1]
	v_add_u32_e32 v142, 0x4000, v155
	v_pk_add_f32 v[110:111], v[110:111], 1.0 op_sel_hi:[1,0]
	v_pk_mul_f32 v[122:123], v[162:163], v[122:123]
	v_exp_f32_e32 v112, v112
	v_exp_f32_e32 v113, v113
	v_exp_f32_e32 v108, v108
	v_exp_f32_e32 v109, v109
	ds_read2_b32 v[162:163], v142 offset1:16
	ds_read2_b32 v[164:165], v142 offset0:128 offset1:144
	v_rcp_f32_e32 v110, v110
	v_rcp_f32_e32 v111, v111
	s_waitcnt vmcnt(5)
	v_mul_f32_e32 v142, 0xbfb8aa3b, v168
	v_pk_fma_f32 v[100:101], v[100:101], s[0:1], v[142:143] op_sel_hi:[1,0,0] neg_lo:[1,0,0] neg_hi:[1,0,0]
	v_pk_add_f32 v[112:113], v[112:113], 1.0 op_sel_hi:[1,0]
	v_exp_f32_e32 v100, v100
	v_exp_f32_e32 v101, v101
	v_pk_fma_f32 v[156:157], v[108:109], v[108:109], 1.0 op_sel_hi:[1,1,0] neg_lo:[1,0,0] neg_hi:[1,0,0]
	v_pk_mul_f32 v[110:111], v[132:133], v[110:111] op_sel_hi:[0,1]
	v_rcp_f32_e32 v112, v112
	v_rcp_f32_e32 v113, v113
	v_sqrt_f32_e32 v156, v156
	v_sqrt_f32_e32 v157, v157
	v_exp_f32_e32 v110, v110
	v_exp_f32_e32 v111, v111
	v_pk_fma_f32 v[114:115], v[114:115], s[0:1], v[154:155] op_sel_hi:[1,0,0] neg_lo:[1,0,0] neg_hi:[1,0,0]
	v_pk_add_f32 v[100:101], v[100:101], 1.0 op_sel_hi:[1,0]
	v_exp_f32_e32 v114, v114
	v_exp_f32_e32 v115, v115
	v_rcp_f32_e32 v100, v100
	v_rcp_f32_e32 v101, v101
	v_pk_fma_f32 v[102:103], v[102:103], s[0:1], v[142:143] op_sel_hi:[1,0,0] neg_lo:[1,0,0] neg_hi:[1,0,0]
	s_waitcnt lgkmcnt(1)
	v_mov_b32_e32 v172, v162
	v_exp_f32_e32 v102, v102
	v_exp_f32_e32 v103, v103
	s_waitcnt lgkmcnt(0)
	v_mov_b32_e32 v173, v164
	v_pk_mul_f32 v[112:113], v[112:113], v[156:157]
	v_pk_fma_f32 v[156:157], v[110:111], v[110:111], 1.0 op_sel_hi:[1,1,0] neg_lo:[1,0,0] neg_hi:[1,0,0]
	v_add_u32_e32 v128, 0x4400, v155
	v_pk_mul_f32 v[112:113], v[172:173], v[112:113]
	v_sqrt_f32_e32 v172, v156
	v_sqrt_f32_e32 v173, v157
	ds_read2_b32 v[156:157], v128 offset1:16
	ds_read2_b32 v[154:155], v128 offset0:128 offset1:144
	s_waitcnt vmcnt(5)
; template <bool FINAL> ...
;     ...
;                 for (int ip = 0; ip < 4; ip += 2) { const int tk = mt * 16 + fq * 4 + ip;
;                     const f32x2 xr2 = (f32x2){acc[mt][0][nt][ip], acc[mt][0][nt][ip + 1]}, xi2 = (f32x2){acc[mt][1][nt][ip], acc[mt][1][nt][ip + 1]};
;                     const f32x2 tr = xr2 * (-1.4426950408889634f) + nbr, ti = xi2 * (-1.4426950408889634f) + nbi;
;                     f32x2 er, ei; er.x = __builtin_amdgcn_exp2f(tr.x); er.y = __builtin_amdgcn_exp2f(tr.y); ei.x = __builtin_amdgcn_exp2f(ti.x); ei.y = __builtin_amdgcn_exp2f(ti.y);
;                     er = er + 1.0f; ei = ei + 1.0f;
;                     f32x2 r, ig; r.x = __builtin_amdgcn_rcpf(er.x); r.y = __builtin_amdgcn_rcpf(er.y); ig.x = __builtin_amdgcn_rcpf(ei.x); ig.y = __builtin_amdgcn_rcpf(ei.y);
;                     const f32x2 la = r * k8;
;                     f32x2 a; a.x = __builtin_amdgcn_exp2f(la.x); a.y = __builtin_amdgcn_exp2f(la.y);
;                     const f32x2 y = 1.0f - a * a;
;                     f32x2 sq; sq.x = __builtin_amdgcn_sqrtf(y.x); sq.y = __builtin_amdgcn_sqrtf(y.y);
;                     const f32x2 xc2 = (f32x2){XCF[tk * 128 + ch], XCF[(tk + 1) * 128 + ch]};
;                     const f32x2 bb = sq * ig * xc2;
;                     acc[mt][0][nt][ip] = a.x; acc[mt][0][nt][ip + 1] = a.y; acc[mt][1][nt][ip] = bb.x; acc[mt][1][nt][ip + 1] = bb.y; } }
;         if (dir) lru_scan<FINAL, true>(acc, HF, SUMS, sbase, hin0, hin1, cq, fr, fq, lane);
;         else     lru_scan<FINAL, false>(acc, HF, SUMS, sbase, hin0, hin1, cq, fr, fq, lane);
	v_mul_f32_e32 v128, 0xbfb8aa3b, v167
	v_pk_add_f32 v[114:115], v[114:115], 1.0 op_sel_hi:[1,0]
	v_pk_fma_f32 v[104:105], v[104:105], s[0:1], v[128:129] op_sel_hi:[1,0,0] neg_lo:[1,0,0] neg_hi:[1,0,0]
	v_pk_mul_f32 v[100:101], v[126:127], v[100:101] op_sel_hi:[0,1]
	v_rcp_f32_e32 v114, v114
	v_rcp_f32_e32 v115, v115
	v_exp_f32_e32 v104, v104
	v_exp_f32_e32 v105, v105
	v_exp_f32_e32 v100, v100
	v_exp_f32_e32 v101, v101
	v_pk_add_f32 v[102:103], v[102:103], 1.0 op_sel_hi:[1,0]
	v_pk_fma_f32 v[92:93], v[92:93], s[0:1], v[142:143] op_sel_hi:[1,0,0] neg_lo:[1,0,0] neg_hi:[1,0,0]
	v_rcp_f32_e32 v102, v102
	v_rcp_f32_e32 v103, v103
	v_exp_f32_e32 v92, v92
	v_exp_f32_e32 v93, v93
	v_pk_mul_f32 v[114:115], v[114:115], v[172:173]
	v_pk_add_f32 v[104:105], v[104:105], 1.0 op_sel_hi:[1,0]
	v_pk_fma_f32 v[172:173], v[100:101], v[100:101], 1.0 op_sel_hi:[1,1,0] neg_lo:[1,0,0] neg_hi:[1,0,0]
	v_rcp_f32_e32 v104, v104
	v_rcp_f32_e32 v105, v105
	v_sqrt_f32_e32 v172, v172
	v_sqrt_f32_e32 v173, v173
	v_pk_fma_f32 v[106:107], v[106:107], s[0:1], v[128:129] op_sel_hi:[1,0,0] neg_lo:[1,0,0] neg_hi:[1,0,0]
	v_pk_mul_f32 v[102:103], v[126:127], v[102:103] op_sel_hi:[0,1]
	v_pk_add_f32 v[92:93], v[92:93], 1.0 op_sel_hi:[1,0]
	v_pk_fma_f32 v[94:95], v[94:95], s[0:1], v[142:143] op_sel_hi:[1,0,0] neg_lo:[1,0,0] neg_hi:[1,0,0]
	v_exp_f32_e32 v106, v106
	v_exp_f32_e32 v107, v107
	v_exp_f32_e32 v102, v102
	v_exp_f32_e32 v103, v103
	v_rcp_f32_e32 v92, v92
	v_rcp_f32_e32 v93, v93
	v_exp_f32_e32 v94, v94
	v_exp_f32_e32 v95, v95
	v_mov_b32_e32 v144, v143
	v_pk_mul_f32 v[104:105], v[104:105], v[172:173]
	v_pk_add_f32 v[106:107], v[106:107], 1.0 op_sel_hi:[1,0]
	v_pk_mul_f32 v[104:105], v[104:105], v[144:145]
	v_pk_fma_f32 v[144:145], v[102:103], v[102:103], 1.0 op_sel_hi:[1,1,0] neg_lo:[1,0,0] neg_hi:[1,0,0]
	v_pk_fma_f32 v[96:97], v[96:97], s[0:1], v[128:129] op_sel_hi:[1,0,0] neg_lo:[1,0,0] neg_hi:[1,0,0]
	v_pk_mul_f32 v[92:93], v[126:127], v[92:93] op_sel_hi:[0,1]
	v_pk_add_f32 v[94:95], v[94:95], 1.0 op_sel_hi:[1,0]
	v_pk_fma_f32 v[84:85], v[84:85], s[0:1], v[142:143] op_sel_hi:[1,0,0] neg_lo:[1,0,0] neg_hi:[1,0,0]
	v_pk_fma_f32 v[86:87], v[86:87], s[0:1], v[142:143] op_sel_hi:[1,0,0] neg_lo:[1,0,0] neg_hi:[1,0,0]
	v_rcp_f32_e32 v106, v106
	v_rcp_f32_e32 v107, v107
	v_sqrt_f32_e32 v144, v144
	v_sqrt_f32_e32 v145, v145
	v_exp_f32_e32 v96, v96
	v_exp_f32_e32 v97, v97
	v_exp_f32_e32 v92, v92
	v_exp_f32_e32 v93, v93
	v_rcp_f32_e32 v94, v94
	v_rcp_f32_e32 v95, v95
	v_exp_f32_e32 v84, v84
	v_exp_f32_e32 v85, v85
	v_exp_f32_e32 v86, v86
	v_exp_f32_e32 v87, v87
	v_pk_mul_f32 v[106:107], v[106:107], v[144:145]
	v_pk_add_f32 v[96:97], v[96:97], 1.0 op_sel_hi:[1,0]
	v_pk_fma_f32 v[144:145], v[92:93], v[92:93], 1.0 op_sel_hi:[1,1,0] neg_lo:[1,0,0] neg_hi:[1,0,0]
	v_pk_fma_f32 v[98:99], v[98:99], s[0:1], v[128:129] op_sel_hi:[1,0,0] neg_lo:[1,0,0] neg_hi:[1,0,0]
	v_pk_mul_f32 v[94:95], v[126:127], v[94:95] op_sel_hi:[0,1]
	v_pk_add_f32 v[84:85], v[84:85], 1.0 op_sel_hi:[1,0]
	v_pk_add_f32 v[86:87], v[86:87], 1.0 op_sel_hi:[1,0]
	v_rcp_f32_e32 v96, v96
	v_rcp_f32_e32 v97, v97
	v_sqrt_f32_e32 v144, v144
	v_sqrt_f32_e32 v145, v145
	v_exp_f32_e32 v98, v98
	v_exp_f32_e32 v99, v99
	v_exp_f32_e32 v94, v94
	v_exp_f32_e32 v95, v95
	v_rcp_f32_e32 v84, v84
	v_rcp_f32_e32 v85, v85
	v_rcp_f32_e32 v86, v86
	v_rcp_f32_e32 v87, v87
	v_pk_mul_f32 v[96:97], v[96:97], v[144:145]
	v_pk_add_f32 v[98:99], v[98:99], 1.0 op_sel_hi:[1,0]
	v_pk_fma_f32 v[144:145], v[94:95], v[94:95], 1.0 op_sel_hi:[1,1,0] neg_lo:[1,0,0] neg_hi:[1,0,0]
	v_pk_fma_f32 v[88:89], v[88:89], s[0:1], v[128:129] op_sel_hi:[1,0,0] neg_lo:[1,0,0] neg_hi:[1,0,0]
	v_pk_mul_f32 v[84:85], v[126:127], v[84:85] op_sel_hi:[0,1]
	v_pk_fma_f32 v[90:91], v[90:91], s[0:1], v[128:129] op_sel_hi:[1,0,0] neg_lo:[1,0,0] neg_hi:[1,0,0]
	v_pk_mul_f32 v[86:87], v[126:127], v[86:87] op_sel_hi:[0,1]
	v_rcp_f32_e32 v98, v98
	v_rcp_f32_e32 v99, v99
	v_sqrt_f32_e32 v144, v144
	v_sqrt_f32_e32 v145, v145
	v_exp_f32_e32 v88, v88
	v_exp_f32_e32 v89, v89
	v_exp_f32_e32 v84, v84
	v_exp_f32_e32 v85, v85
	v_exp_f32_e32 v90, v90
	v_exp_f32_e32 v91, v91
	v_exp_f32_e32 v86, v86
	v_exp_f32_e32 v87, v87
	v_pk_mul_f32 v[98:99], v[98:99], v[144:145]
	v_pk_add_f32 v[88:89], v[88:89], 1.0 op_sel_hi:[1,0]
	v_pk_fma_f32 v[144:145], v[84:85], v[84:85], 1.0 op_sel_hi:[1,1,0] neg_lo:[1,0,0] neg_hi:[1,0,0]
	v_pk_add_f32 v[90:91], v[90:91], 1.0 op_sel_hi:[1,0]
	v_pk_fma_f32 v[142:143], v[86:87], v[86:87], 1.0 op_sel_hi:[1,1,0] neg_lo:[1,0,0] neg_hi:[1,0,0]
	v_rcp_f32_e32 v88, v88
	v_rcp_f32_e32 v89, v89
	v_sqrt_f32_e32 v144, v144
	v_sqrt_f32_e32 v145, v145
	v_rcp_f32_e32 v90, v90
	v_rcp_f32_e32 v91, v91
	v_sqrt_f32_e32 v142, v142
	v_sqrt_f32_e32 v143, v143
	s_waitcnt lgkmcnt(1)
	v_mov_b32_e32 v174, v156
	s_waitcnt lgkmcnt(0)
	v_mov_b32_e32 v175, v154
	v_mov_b32_e32 v148, v147
	v_mov_b32_e32 v152, v151
	v_mov_b32_e32 v160, v159
	v_mov_b32_e32 v164, v163
	v_pk_mul_f32 v[88:89], v[88:89], v[144:145]
	v_mov_b32_e32 v154, v157
	v_pk_mul_f32 v[90:91], v[90:91], v[142:143]
	v_pk_mul_f32 v[114:115], v[174:175], v[114:115]
	v_pk_mul_f32 v[106:107], v[106:107], v[148:149]
	v_pk_mul_f32 v[96:97], v[96:97], v[152:153]
	v_pk_mul_f32 v[98:99], v[98:99], v[160:161]
	v_pk_mul_f32 v[88:89], v[164:165], v[88:89]
	v_pk_mul_f32 v[90:91], v[90:91], v[154:155]
	s_cbranch_vccnz .LBB0_647
; #define LAS __attribute__((address_space(3)))
; template <bool FINAL, bool REV>
; __device__ __forceinline__ void lru_scan(const f32x4 (&acc)[3][2][2], LAS float* HF, f32x2* SUMS, size_t sbase, float hin0, float hin1, int cq, int fr, int fq, int lane) {
;     const int rank = REV ? 3 - fq : fq;
;     const int src1 = (REV ? lane + 16 : lane - 16) & 63, src2 = (REV ? lane + 32 : lane - 32) & 63, srcT = REV ? fr : fr + 48;
; #pragma unroll
;     for (int nt = 0; nt < 2; ++nt) {
;         float Pe[3], Qe[3], Pt[3], Qt[3];
; #pragma unroll
;         for (int mt = 0; mt < 3; ++mt) { float p = 1.f, q = 0.f;
; #pragma unroll
;             for (int ii = 0; ii < 4; ++ii) { const int i = REV ? 3 - ii : ii; const float a = acc[mt][0][nt][i]; q = a * q + acc[mt][1][nt][i]; p *= a; }
;             { const float pp = __shfl(p, src1), qp = __shfl(q, src1); if (rank >= 1) { q = qp * p + q; p = pp * p; } }
;             { const float pp = __shfl(p, src2), qp = __shfl(q, src2); if (rank >= 2) { q = qp * p + q; p = pp * p; } }
;             Pt[mt] = __shfl(p, srcT); Qt[mt] = __shfl(q, srcT);
;             if (FINAL) { const float pe = __shfl(p, src1), qe = __shfl(q, src1); Pe[mt] = rank >= 1 ? pe : 1.f; Qe[mt] = rank >= 1 ? qe : 0.f; } }
;         if (!FINAL) { float A = 1.f, Bv = 0.f;
; #pragma unroll
;             for (int mm = 0; mm < 3; ++mm) { const int mt = REV ? 2 - mm : mm; Bv = Bv * Pt[mt] + Qt[mt]; A *= Pt[mt]; }
;             if (fq == 0) SUMS[sbase + 16 * nt] = (f32x2){A, Bv};
	v_and_b32_e32 v143, 64, v235
	v_xor_b32_e32 v128, 2, v125
	v_cmp_eq_u32_e64 s[38:39], 3, v125
	v_or_b32_e32 v125, v143, v170
	v_lshlrev_b32_e32 v125, 2, v125
	v_xor_b32_e32 v148, 0x80, v125
	v_or_b32_e32 v125, v143, v169
	v_cmp_lt_u32_e32 vcc, 1, v128
	v_lshlrev_b32_e32 v128, 2, v125
	v_fma_f32 v125, 0, v139, v141
	v_add_u32_e32 v142, 16, v124
	v_fma_f32 v125, v138, v125, v140
	v_and_or_b32 v142, v142, 63, v143
	v_fma_f32 v125, v135, v125, v137
	v_lshlrev_b32_e32 v149, 2, v142
	v_mul_f32_e32 v142, v139, v138
	v_fma_f32 v125, v134, v125, v136
	v_mul_f32_e32 v142, v135, v142
	ds_bpermute_b32 v144, v149, v125
	v_mul_f32_e32 v142, v134, v142
	ds_bpermute_b32 v143, v149, v142
	s_waitcnt lgkmcnt(1)
	v_fma_f32 v144, v142, v144, v125
	v_cndmask_b32_e64 v125, v144, v125, s[38:39]
	s_waitcnt lgkmcnt(0)
	v_mul_f32_e32 v143, v142, v143
	ds_bpermute_b32 v144, v148, v125
	v_cndmask_b32_e64 v142, v143, v142, s[38:39]
	ds_bpermute_b32 v143, v148, v142
	s_waitcnt lgkmcnt(1)
	v_fma_f32 v144, v142, v144, v125
	v_cndmask_b32_e32 v125, v125, v144, vcc
	s_waitcnt lgkmcnt(0)
	v_mul_f32_e32 v143, v142, v143
	ds_bpermute_b32 v145, v128, v125
	v_fma_f32 v125, 0, v119, v123
	v_cndmask_b32_e32 v142, v142, v143, vcc
	v_fma_f32 v125, v118, v125, v122
	ds_bpermute_b32 v143, v128, v142
	v_mul_f32_e32 v142, v119, v118
	v_fma_f32 v125, v117, v125, v121
	v_mul_f32_e32 v142, v117, v142
	v_fma_f32 v125, v116, v125, v120
	v_mul_f32_e32 v142, v116, v142
	ds_bpermute_b32 v146, v149, v125
	ds_bpermute_b32 v144, v149, v142
	s_waitcnt lgkmcnt(1)
	v_fma_f32 v146, v142, v146, v125
	s_waitcnt lgkmcnt(0)
	v_mul_f32_e32 v144, v142, v144
	v_cndmask_b32_e64 v125, v146, v125, s[38:39]
	v_cndmask_b32_e64 v142, v144, v142, s[38:39]
	ds_bpermute_b32 v146, v148, v125
	ds_bpermute_b32 v144, v148, v142
	s_waitcnt lgkmcnt(1)
	v_fma_f32 v146, v142, v146, v125
	s_waitcnt lgkmcnt(0)
	v_mul_f32_e32 v144, v142, v144
	v_cndmask_b32_e32 v125, v125, v146, vcc
	v_cndmask_b32_e32 v142, v142, v144, vcc
	ds_bpermute_b32 v147, v128, v125
	v_fma_f32 v125, 0, v111, v115
	ds_bpermute_b32 v146, v128, v142
	v_fma_f32 v125, v110, v125, v114
	v_mul_f32_e32 v142, v111, v110
	v_fma_f32 v125, v109, v125, v113
	v_mul_f32_e32 v142, v109, v142
	v_fma_f32 v125, v108, v125, v112
	v_mul_f32_e32 v142, v108, v142
	ds_bpermute_b32 v144, v149, v142
	ds_bpermute_b32 v150, v149, v125
	s_waitcnt lgkmcnt(1)
	v_mul_f32_e32 v144, v142, v144
	s_waitcnt lgkmcnt(0)
	v_fma_f32 v150, v142, v150, v125
	v_cndmask_b32_e64 v125, v150, v125, s[38:39]
	v_cndmask_b32_e64 v142, v144, v142, s[38:39]
	ds_bpermute_b32 v144, v148, v142
	ds_bpermute_b32 v150, v148, v125
	s_waitcnt lgkmcnt(1)
	v_mul_f32_e32 v144, v142, v144
	s_waitcnt lgkmcnt(0)
	v_fma_f32 v150, v142, v150, v125
	v_cndmask_b32_e32 v125, v125, v150, vcc
	v_cndmask_b32_e32 v142, v142, v144, vcc
	ds_bpermute_b32 v142, v128, v142
	ds_bpermute_b32 v125, v128, v125
	s_and_saveexec_b64 s[28:29], s[36:37]
	s_cbranch_execz .LBB0_644
	s_waitcnt lgkmcnt(0)
	v_fmac_f32_e32 v125, 0, v142
	v_readlane_b32 s0, v253, 44
	v_mov_b32_e32 v144, v143
	v_fmac_f32_e32 v147, v125, v146
	v_mul_f32_e32 v125, v146, v142
	v_readlane_b32 s1, v253, 45
	v_mul_f32_e32 v152, v125, v143
	v_pk_fma_f32 v[142:143], v[146:147], v[142:143], v[144:145]
	v_lshl_add_u64 v[150:151], v[130:131], 3, s[0:1]
	v_mov_b32_e32 v153, v143
	global_store_dwordx2 v[150:151], v[152:153], off
